# seams 1-2 and 7-9 as group barriers with pairwise guards: a group also waits for the two groups whose XN / Y / ONSA rows its SKK / XN2 writes lie over; RWKV-prep chunks re-dealt to own group rows
# baseline (speedup 1.0000x reference)
.LBB0_1696:
	s_cmp_gt_i32 s87, 2
	s_cselect_b64 s[2:3], -1, 0
	s_and_b64 s[0:1], s[0:1], s[2:3]
	s_andn2_b64 vcc, exec, s[0:1]
	s_cbranch_vccnz .LBB0_1750
	s_waitcnt vmcnt(0)
	s_waitcnt vmcnt(0) lgkmcnt(0)
	s_barrier
	s_mov_b64 s[0:1], exec
	v_readlane_b32 s4, v251, 1
	v_readlane_b32 s5, v251, 2
	s_and_b64 s[4:5], s[0:1], s[4:5]
	s_mov_b64 exec, s[4:5]
	s_cbranch_execz .LBB0_1749
	s_waitcnt vmcnt(0) expcnt(0) lgkmcnt(0)
	buffer_inv sc1
	s_and_b32 s4, s90, 7
	s_lshl_b32 s4, s4, 8
	s_add_i32 s4, s4, 0x3600
	v_mov_b32_e32 v0, s4
	v_mov_b32_e32 v2, 1
	global_atomic_add v0, v0, v2, s[96:97] sc0
	s_nop 0
	v_mov_b32_e32 v2, 0x3e00
	global_load_dword v2, v2, s[96:97] sc1
	s_waitcnt vmcnt(0)
	v_readfirstlane_b32 s5, v2
	v_readfirstlane_b32 vcc_lo, v0
	s_cmp_lg_u32 s5, 0
	s_cbranch_scc1 .Lgb_orig5
	s_or_b32 s5, vcc_lo, 31
	s_add_i32 s5, s5, 1
	s_mov_b32 vcc_hi, 0
.Lgb_poll5:
	s_sub_i32 vcc_lo, s4, 0x3600
	s_lshr_b32 vcc_lo, vcc_lo, 1
	s_and_b32 vcc_lo, vcc_lo, 0x300
	s_add_i32 vcc_lo, vcc_lo, 0x3600
	v_mov_b32_e32 v0, s4
	v_mov_b32_e32 v1, vcc_lo
	v_add_u32_e32 v3, 0x400, v1
	global_load_dword v0, v0, s[96:97] sc1
	global_load_dword v1, v1, s[96:97] sc1
	global_load_dword v3, v3, s[96:97] sc1
	s_waitcnt vmcnt(0)
	v_min_u32_e32 v0, v0, v1
	v_min_u32_e32 v0, v0, v3
	s_nop 1
	v_readfirstlane_b32 vcc_lo, v0
	s_sub_i32 vcc_lo, vcc_lo, s5
	s_cmp_ge_i32 vcc_lo, 0
	s_cbranch_scc1 .Lgb_done5
	s_add_i32 vcc_hi, vcc_hi, 1
	s_cmp_lt_u32 vcc_hi, 0x40000
	s_cbranch_scc0 .Lgb_done5
	s_sleep 1
	s_branch .Lgb_poll5

.LBB0_2265:
	s_cmp_lt_i32 s87, 9
	s_cselect_b64 s[2:3], -1, 0
	s_xor_b64 s[0:1], s[0:1], -1
	s_or_b64 s[0:1], s[0:1], s[2:3]
	s_and_b64 vcc, exec, s[0:1]
	s_cbranch_vccnz .LBB0_2319
	s_waitcnt vmcnt(0)
	s_waitcnt vmcnt(0)
	s_barrier
	s_mov_b64 s[0:1], exec
	v_readlane_b32 s2, v251, 1
	v_readlane_b32 s3, v251, 2
	s_and_b64 s[2:3], s[0:1], s[2:3]
	s_mov_b64 exec, s[2:3]
	s_cbranch_execz .LBB0_2318
	s_waitcnt vmcnt(0) expcnt(0) lgkmcnt(0)
	buffer_inv sc1
	s_and_b32 s2, s90, 7
	s_lshl_b32 s2, s2, 8
	s_add_i32 s2, s2, 0x3600
	v_mov_b32_e32 v0, s2
	v_mov_b32_e32 v2, 1
	global_atomic_add v0, v0, v2, s[96:97] sc0
	s_nop 0
	v_mov_b32_e32 v2, 0x3e00
	global_load_dword v2, v2, s[96:97] sc1
	s_waitcnt vmcnt(0)
	v_readfirstlane_b32 s3, v2
	v_readfirstlane_b32 vcc_lo, v0
	s_cmp_lg_u32 s3, 0
	s_cbranch_scc1 .Lgb_orig4
	s_or_b32 s3, vcc_lo, 31
	s_add_i32 s3, s3, 1
	s_mov_b32 vcc_hi, 0
.Lgb_poll4:
	s_sub_i32 vcc_lo, s2, 0x3600
	s_lshl_b32 vcc_lo, vcc_lo, 1
	s_and_b32 vcc_lo, vcc_lo, 0x700
	s_add_i32 vcc_lo, vcc_lo, 0x3600
	v_mov_b32_e32 v0, s2
	v_mov_b32_e32 v1, vcc_lo
	v_add_u32_e32 v3, 0x100, v1
	global_load_dword v0, v0, s[96:97] sc1
	global_load_dword v1, v1, s[96:97] sc1
	global_load_dword v3, v3, s[96:97] sc1
	s_waitcnt vmcnt(0)
	v_min_u32_e32 v0, v0, v1
	v_min_u32_e32 v0, v0, v3
	s_nop 1
	v_readfirstlane_b32 vcc_lo, v0
	s_sub_i32 vcc_lo, vcc_lo, s3
	s_cmp_ge_i32 vcc_lo, 0
	s_cbranch_scc1 .Lgb_done4
	s_add_i32 vcc_hi, vcc_hi, 1
	s_cmp_lt_u32 vcc_hi, 0x40000
	s_cbranch_scc0 .Lgb_done4
	s_sleep 1
	s_branch .Lgb_poll4
